# phase_h (rmsnorm+adaLN -> bf16) rewritten by hand: 2 rows per iteration, all gain/shift/scale loads issued with the x loads, DPP+permlane reduction; on top of mode-B bias read batching
# speedup vs baseline: 1.0095x; 1.0095x over previous
; __device__ __forceinline__ int otid() { int t = threadIdx.x; asm volatile("" : "+v"(t)); return t; }
; __device__ __forceinline__ void phase_h(const Params& p, int c, int l, bf16_t* H) {
;     const int wave = otid() >> 6, lane = otid() & 63;
;     const int row0 = chunk_row0(c), n = chunk_rows(c);
;     const float* lng = p.in[4] + l * DM;
;     const float* mod_l = (const float*)(p.ws + WS_MOD) + (size_t)l * NSEQ * 3072;
;     for (int row = blockIdx.x * 8 + wave; row < n; row += gridDim.x * 8) {
;         const int g = row0 + row;
;         const float* xr = (l == 0) ? ((g < NPROMPT) ? p.in[0] + (size_t)g * DM : p.in[1] + (size_t)(g - NPROMPT) * DM) : p.out + (size_t)g * DM;
;         f32x4 v[4]; float ss = 0.f;
; #pragma unroll
;         for (int j = 0; j < 4; ++j) { v[j] = *(const f32x4*)(xr + j * 256 + lane * 4); ss += v[j][0] * v[j][0] + v[j][1] * v[j][1] + v[j][2] * v[j][2] + v[j][3] * v[j][3]; }
;         ss = wave_sum(ss);
;         const float rstd = rsqrtf(ss * (1.f / 1024.f) + EPS);
;         const float* md = mod_l + (size_t)seq_of(g) * 3072;
; #pragma unroll
;         for (int j = 0; j < 4; ++j) {
;             const int col = j * 256 + lane * 4;
;             const f32x4 gg = *(const f32x4*)(lng + col), sh = *(const f32x4*)(md + col), sc = *(const f32x4*)(md + 1024 + col);
.LBB0_101:
	v_readlane_b32 s2, v255, 15
	s_cmp_gt_u32 s2, 17
	s_cselect_b32 s7, 1, 0
	s_cmp_eq_u32 s2, 17
	s_cselect_b32 s7, 1, s7
	s_cmp_gt_u32 s2, 17
	s_cselect_b32 s3, 18, 2
	s_sub_i32 s3, s2, s3
	s_mul_i32 s3, s3, 0x3334
	s_lshr_b32 s3, s3, 16
	s_add_i32 s3, s3, 1
	s_cmp_eq_u32 s2, 1
	s_cselect_b32 s3, 0, s3
	s_cmp_eq_u32 s2, 17
	s_cselect_b32 s3, 0, s3
	s_lshl_b32 s6, s3, 15
	s_cmp_eq_u32 s3, 2
	s_movk_i32 s4, 0x4000
	s_cselect_b32 s3, s4, 0x8000
	v_readlane_b32 s4, v252, 21
	v_readlane_b32 s5, v252, 22
	s_nop 0
	s_load_dword s5, s[4:5], 0x0
	v_lshlrev_b32_e32 v2, 4, v219
	v_lshlrev_b32_e32 v3, 3, v219
	v_xor_b32_e32 v120, 16, v219
	v_lshlrev_b32_e32 v120, 2, v120
	v_readlane_b32 s2, v253, 43
	v_lshrrev_b32_e32 v0, 6, v251
	s_nop 0
	v_readfirstlane_b32 s4, v0
	s_add_i32 s2, s2, s4
	v_readlane_b32 s8, v252, 15
	v_readlane_b32 s9, v252, 16
	s_mul_i32 s4, s7, 0x6c000
	s_add_u32 s10, s8, 0x320dd900
	s_addc_u32 s11, s9, 0
	s_add_u32 s8, s8, 0x1d00000
	s_addc_u32 s9, s9, 0
	s_add_u32 s8, s8, s4
	s_addc_u32 s9, s9, 0
	v_readlane_b32 s16, v253, 52
	v_readlane_b32 s17, v253, 53
	s_lshl_b32 s4, s7, 12
	s_add_u32 s16, s16, s4
	s_addc_u32 s17, s17, 0
	s_nop 3
	global_load_dwordx4 v[4:7], v2, s[16:17] offset:0
	global_load_dwordx4 v[8:11], v2, s[16:17] offset:1024
	global_load_dwordx4 v[12:15], v2, s[16:17] offset:2048
	global_load_dwordx4 v[16:19], v2, s[16:17] offset:3072
	s_waitcnt lgkmcnt(0)
	s_lshl_b32 s5, s5, 3
	s_cmp_ge_i32 s2, s3
	s_cbranch_scc1 .Lh1_done
.Lh1_loop:
	s_add_i32 s24, s2, s6
	s_cmp_eq_u32 s7, 1
	s_cbranch_scc1 .Lh1_x1_12
	s_cmp_lt_u32 s24, 0x4000
	s_cbranch_scc1 .Lh1_xp_12
	s_sub_i32 s24, s24, 0x4000
	v_readlane_b32 s12, v253, 46
	v_readlane_b32 s13, v253, 47
	s_branch .Lh1_xe_12
.Lh1_xp_12:
	v_readlane_b32 s12, v253, 44
	v_readlane_b32 s13, v253, 45
	s_branch .Lh1_xe_12
.Lh1_x1_12:
	v_readlane_b32 s12, v252, 13
	v_readlane_b32 s13, v252, 14
.Lh1_xe_12:
	s_mov_b32 s25, 0
	s_lshl_b64 s[24:25], s[24:25], 12
	s_add_u32 s12, s12, s24
	s_addc_u32 s13, s13, s25
	s_add_i32 s24, s2, s6
	s_lshr_b32 s25, s24, 12
	s_sub_i32 s24, s24, 0x4000
	s_lshr_b32 s24, s24, 11
	s_add_i32 s24, s24, 4
	s_add_i32 s14, s2, s6
	s_cmp_lt_u32 s14, 0x4000
	s_cselect_b32 s24, s25, s24
	s_mul_i32 s24, s24, 0x3000
	s_add_u32 s14, s8, s24
	s_addc_u32 s15, s9, 0
	s_nop 1
	global_load_dwordx4 v[20:23], v2, s[12:13] offset:0
	global_load_dwordx4 v[24:27], v2, s[12:13] offset:1024
	global_load_dwordx4 v[28:31], v2, s[12:13] offset:2048
	global_load_dwordx4 v[32:35], v2, s[12:13] offset:3072
	global_load_dwordx4 v[36:39], v2, s[14:15] offset:0
	global_load_dwordx4 v[40:43], v2, s[14:15] offset:1024
	global_load_dwordx4 v[44:47], v2, s[14:15] offset:2048
	global_load_dwordx4 v[48:51], v2, s[14:15] offset:3072
	s_add_u32 s14, s14, 0x1000
	s_addc_u32 s15, s15, 0
	global_load_dwordx4 v[52:55], v2, s[14:15] offset:0
	global_load_dwordx4 v[56:59], v2, s[14:15] offset:1024
	global_load_dwordx4 v[60:63], v2, s[14:15] offset:2048
	global_load_dwordx4 v[64:67], v2, s[14:15] offset:3072
	s_add_i32 s4, s2, s5
	s_cmp_ge_i32 s4, s3
	s_cbranch_scc1 .Lh1_noB1
	s_add_i32 s24, s4, s6
	s_cmp_eq_u32 s7, 1
	s_cbranch_scc1 .Lh1_x1_16
	s_cmp_lt_u32 s24, 0x4000
	s_cbranch_scc1 .Lh1_xp_16
	s_sub_i32 s24, s24, 0x4000
	v_readlane_b32 s16, v253, 46
	v_readlane_b32 s17, v253, 47
	s_branch .Lh1_xe_16
.Lh1_xp_16:
	v_readlane_b32 s16, v253, 44
	v_readlane_b32 s17, v253, 45
	s_branch .Lh1_xe_16
.Lh1_x1_16:
	v_readlane_b32 s16, v252, 13
	v_readlane_b32 s17, v252, 14
.Lh1_xe_16:
	s_mov_b32 s25, 0
	s_lshl_b64 s[24:25], s[24:25], 12
	s_add_u32 s16, s16, s24
	s_addc_u32 s17, s17, s25
	s_add_i32 s24, s4, s6
	s_lshr_b32 s25, s24, 12
	s_sub_i32 s24, s24, 0x4000
	s_lshr_b32 s24, s24, 11
	s_add_i32 s24, s24, 4
	s_add_i32 s18, s4, s6
	s_cmp_lt_u32 s18, 0x4000
	s_cselect_b32 s24, s25, s24
	s_mul_i32 s24, s24, 0x3000
	s_add_u32 s18, s8, s24
	s_addc_u32 s19, s9, 0
	s_nop 1
	global_load_dwordx4 v[68:71], v2, s[16:17] offset:0
	global_load_dwordx4 v[72:75], v2, s[16:17] offset:1024
	global_load_dwordx4 v[76:79], v2, s[16:17] offset:2048
	global_load_dwordx4 v[80:83], v2, s[16:17] offset:3072
	global_load_dwordx4 v[84:87], v2, s[18:19] offset:0
	global_load_dwordx4 v[88:91], v2, s[18:19] offset:1024
	global_load_dwordx4 v[92:95], v2, s[18:19] offset:2048
	global_load_dwordx4 v[96:99], v2, s[18:19] offset:3072
	s_add_u32 s18, s18, 0x1000
	s_addc_u32 s19, s19, 0
	global_load_dwordx4 v[100:103], v2, s[18:19] offset:0
	global_load_dwordx4 v[104:107], v2, s[18:19] offset:1024
	global_load_dwordx4 v[108:111], v2, s[18:19] offset:2048
	global_load_dwordx4 v[112:115], v2, s[18:19] offset:3072
; __device__ __forceinline__ unsigned pk2(float lo, float hi) { f32x2 v = {lo, hi}; bf16x2_t b = __builtin_convertvector(v, bf16x2_t); return __builtin_bit_cast(unsigned, b); }
; __device__ __forceinline__ void phase_h(const Params& p, int c, int l, bf16_t* H) {
;     ...
;         f32x4 v[4]; float ss = 0.f;
; #pragma unroll
;         for (int j = 0; j < 4; ++j) { v[j] = *(const f32x4*)(xr + j * 256 + lane * 4); ss += v[j][0] * v[j][0] + v[j][1] * v[j][1] + v[j][2] * v[j][2] + v[j][3] * v[j][3]; }
;         ss = wave_sum(ss);
;         const float rstd = rsqrtf(ss * (1.f / 1024.f) + EPS);
;         const float* md = mod_l + (size_t)seq_of(g) * 3072;
; #pragma unroll
;         for (int j = 0; j < 4; ++j) {
;             const int col = j * 256 + lane * 4;
;             const f32x4 gg = *(const f32x4*)(lng + col), sh = *(const f32x4*)(md + col), sc = *(const f32x4*)(md + 1024 + col);
;             const f32x4 h = v[j] * rstd * gg * (sc + 1.0f) + sh;
;             u32x2 o; o.x = pk2(h[0], h[1]); o.y = pk2(h[2], h[3]);
;             *(u32x2*)(H + (size_t)row * DM + col) = o;
;         }
.Lh1_noB1:
	s_waitcnt vmcnt(0)
	s_mov_b32 s24, s2
	s_mov_b32 s25, 0
	s_lshl_b64 s[24:25], s[24:25], 11
	s_add_u32 s12, s10, s24
	s_addc_u32 s13, s11, s25
	v_mul_f32_e32 v122, v20, v20
	v_mul_f32_e32 v123, v24, v24
	v_mul_f32_e32 v124, v28, v28
	v_mul_f32_e32 v125, v32, v32
	v_fmac_f32_e32 v122, v21, v21
	v_fmac_f32_e32 v123, v25, v25
	v_fmac_f32_e32 v124, v29, v29
	v_fmac_f32_e32 v125, v33, v33
	v_fmac_f32_e32 v122, v22, v22
	v_fmac_f32_e32 v123, v26, v26
	v_fmac_f32_e32 v124, v30, v30
	v_fmac_f32_e32 v125, v34, v34
	v_fmac_f32_e32 v122, v23, v23
	v_fmac_f32_e32 v123, v27, v27
	v_fmac_f32_e32 v124, v31, v31
	v_fmac_f32_e32 v125, v35, v35
	v_add_f32_e32 v122, v122, v123
	v_add_f32_e32 v124, v124, v125
	v_add_f32_e32 v116, v122, v124
	s_nop 1
	v_add_f32_dpp v117, v116, v116 quad_perm:[1,0,3,2] row_mask:0xf bank_mask:0xf
	s_nop 1
	v_add_f32_dpp v116, v117, v117 quad_perm:[2,3,0,1] row_mask:0xf bank_mask:0xf
	s_nop 1
	v_add_f32_dpp v117, v116, v116 row_half_mirror row_mask:0xf bank_mask:0xf
	s_nop 1
	v_add_f32_dpp v116, v117, v117 row_mirror row_mask:0xf bank_mask:0xf
	s_nop 0
	ds_bpermute_b32 v117, v120, v116
	s_waitcnt lgkmcnt(0)
	v_add_f32_e32 v116, v116, v117
	v_mov_b32_e32 v117, v116
	s_nop 1
	v_permlane32_swap_b32_e32 v116, v117
	s_nop 1
	v_add_f32_e32 v116, v116, v117
	v_fmamk_f32 v116, v116, 0x3a800000, v218
	v_rsq_f32_e32 v118, v116
	v_pk_add_f32 v[52:53], v[52:53], 1.0 op_sel_hi:[1,0]
	v_pk_add_f32 v[54:55], v[54:55], 1.0 op_sel_hi:[1,0]
	v_pk_add_f32 v[56:57], v[56:57], 1.0 op_sel_hi:[1,0]
	v_pk_add_f32 v[58:59], v[58:59], 1.0 op_sel_hi:[1,0]
	v_pk_add_f32 v[60:61], v[60:61], 1.0 op_sel_hi:[1,0]
	v_pk_add_f32 v[62:63], v[62:63], 1.0 op_sel_hi:[1,0]
	v_pk_add_f32 v[64:65], v[64:65], 1.0 op_sel_hi:[1,0]
	v_pk_add_f32 v[66:67], v[66:67], 1.0 op_sel_hi:[1,0]
	v_pk_mul_f32 v[20:21], v[20:21], v[118:119] op_sel_hi:[1,0]
	v_pk_mul_f32 v[22:23], v[22:23], v[118:119] op_sel_hi:[1,0]
	v_pk_mul_f32 v[24:25], v[24:25], v[118:119] op_sel_hi:[1,0]
	v_pk_mul_f32 v[26:27], v[26:27], v[118:119] op_sel_hi:[1,0]
	v_pk_mul_f32 v[28:29], v[28:29], v[118:119] op_sel_hi:[1,0]
	v_pk_mul_f32 v[30:31], v[30:31], v[118:119] op_sel_hi:[1,0]
	v_pk_mul_f32 v[32:33], v[32:33], v[118:119] op_sel_hi:[1,0]
	v_pk_mul_f32 v[34:35], v[34:35], v[118:119] op_sel_hi:[1,0]
	v_pk_mul_f32 v[20:21], v[4:5], v[20:21]
	v_pk_mul_f32 v[22:23], v[6:7], v[22:23]
	v_pk_mul_f32 v[24:25], v[8:9], v[24:25]
	v_pk_mul_f32 v[26:27], v[10:11], v[26:27]
	v_pk_mul_f32 v[28:29], v[12:13], v[28:29]
	v_pk_mul_f32 v[30:31], v[14:15], v[30:31]
	v_pk_mul_f32 v[32:33], v[16:17], v[32:33]
	v_pk_mul_f32 v[34:35], v[18:19], v[34:35]
	v_pk_fma_f32 v[20:21], v[52:53], v[20:21], v[36:37]
	v_pk_fma_f32 v[22:23], v[54:55], v[22:23], v[38:39]
	v_pk_fma_f32 v[24:25], v[56:57], v[24:25], v[40:41]
	v_pk_fma_f32 v[26:27], v[58:59], v[26:27], v[42:43]
	v_pk_fma_f32 v[28:29], v[60:61], v[28:29], v[44:45]
	v_pk_fma_f32 v[30:31], v[62:63], v[30:31], v[46:47]
	v_pk_fma_f32 v[32:33], v[64:65], v[32:33], v[48:49]
	v_pk_fma_f32 v[34:35], v[66:67], v[34:35], v[50:51]
	v_cvt_pk_bf16_f32 v20, v20, v21
	v_cvt_pk_bf16_f32 v21, v22, v23
	v_cvt_pk_bf16_f32 v24, v24, v25
	v_cvt_pk_bf16_f32 v25, v26, v27
	v_cvt_pk_bf16_f32 v28, v28, v29
	v_cvt_pk_bf16_f32 v29, v30, v31
	v_cvt_pk_bf16_f32 v32, v32, v33
	v_cvt_pk_bf16_f32 v33, v34, v35
	s_nop 1
	global_store_dwordx2 v3, v[20:21], s[12:13] offset:0
	global_store_dwordx2 v3, v[24:25], s[12:13] offset:512
	global_store_dwordx2 v3, v[28:29], s[12:13] offset:1024
	global_store_dwordx2 v3, v[32:33], s[12:13] offset:1536
	s_add_i32 s4, s2, s5
	s_cmp_ge_i32 s4, s3
	s_cbranch_scc1 .Lh1_noB2
; __device__ __forceinline__ unsigned pk2(float lo, float hi) { f32x2 v = {lo, hi}; bf16x2_t b = __builtin_convertvector(v, bf16x2_t); return __builtin_bit_cast(unsigned, b); }
; __device__ __forceinline__ void phase_h(const Params& p, int c, int l, bf16_t* H) {
;     ...
;     for (int row = blockIdx.x * 8 + wave; row < n; row += gridDim.x * 8) {
;         const int g = row0 + row;
;         const float* xr = (l == 0) ? ((g < NPROMPT) ? p.in[0] + (size_t)g * DM : p.in[1] + (size_t)(g - NPROMPT) * DM) : p.out + (size_t)g * DM;
;         f32x4 v[4]; float ss = 0.f;
; #pragma unroll
;         for (int j = 0; j < 4; ++j) { v[j] = *(const f32x4*)(xr + j * 256 + lane * 4); ss += v[j][0] * v[j][0] + v[j][1] * v[j][1] + v[j][2] * v[j][2] + v[j][3] * v[j][3]; }
;         ss = wave_sum(ss);
;         const float rstd = rsqrtf(ss * (1.f / 1024.f) + EPS);
;         const float* md = mod_l + (size_t)seq_of(g) * 3072;
; #pragma unroll
;         for (int j = 0; j < 4; ++j) {
;             const int col = j * 256 + lane * 4;
;             const f32x4 gg = *(const f32x4*)(lng + col), sh = *(const f32x4*)(md + col), sc = *(const f32x4*)(md + 1024 + col);
;             const f32x4 h = v[j] * rstd * gg * (sc + 1.0f) + sh;
;             u32x2 o; o.x = pk2(h[0], h[1]); o.y = pk2(h[2], h[3]);
;             *(u32x2*)(H + (size_t)row * DM + col) = o;
;         }
;     }
	s_mov_b32 s24, s4
	s_mov_b32 s25, 0
	s_lshl_b64 s[24:25], s[24:25], 11
	s_add_u32 s16, s10, s24
	s_addc_u32 s17, s11, s25
	v_mul_f32_e32 v122, v68, v68
	v_mul_f32_e32 v123, v72, v72
	v_mul_f32_e32 v124, v76, v76
	v_mul_f32_e32 v125, v80, v80
	v_fmac_f32_e32 v122, v69, v69
	v_fmac_f32_e32 v123, v73, v73
	v_fmac_f32_e32 v124, v77, v77
	v_fmac_f32_e32 v125, v81, v81
	v_fmac_f32_e32 v122, v70, v70
	v_fmac_f32_e32 v123, v74, v74
	v_fmac_f32_e32 v124, v78, v78
	v_fmac_f32_e32 v125, v82, v82
	v_fmac_f32_e32 v122, v71, v71
	v_fmac_f32_e32 v123, v75, v75
	v_fmac_f32_e32 v124, v79, v79
	v_fmac_f32_e32 v125, v83, v83
	v_add_f32_e32 v122, v122, v123
	v_add_f32_e32 v124, v124, v125
	v_add_f32_e32 v116, v122, v124
	s_nop 1
	v_add_f32_dpp v117, v116, v116 quad_perm:[1,0,3,2] row_mask:0xf bank_mask:0xf
	s_nop 1
	v_add_f32_dpp v116, v117, v117 quad_perm:[2,3,0,1] row_mask:0xf bank_mask:0xf
	s_nop 1
	v_add_f32_dpp v117, v116, v116 row_half_mirror row_mask:0xf bank_mask:0xf
	s_nop 1
	v_add_f32_dpp v116, v117, v117 row_mirror row_mask:0xf bank_mask:0xf
	s_nop 0
	ds_bpermute_b32 v117, v120, v116
	s_waitcnt lgkmcnt(0)
	v_add_f32_e32 v116, v116, v117
	v_mov_b32_e32 v117, v116
	s_nop 1
	v_permlane32_swap_b32_e32 v116, v117
	s_nop 1
	v_add_f32_e32 v116, v116, v117
	v_fmamk_f32 v116, v116, 0x3a800000, v218
	v_rsq_f32_e32 v118, v116
	v_pk_add_f32 v[100:101], v[100:101], 1.0 op_sel_hi:[1,0]
	v_pk_add_f32 v[102:103], v[102:103], 1.0 op_sel_hi:[1,0]
	v_pk_add_f32 v[104:105], v[104:105], 1.0 op_sel_hi:[1,0]
	v_pk_add_f32 v[106:107], v[106:107], 1.0 op_sel_hi:[1,0]
	v_pk_add_f32 v[108:109], v[108:109], 1.0 op_sel_hi:[1,0]
	v_pk_add_f32 v[110:111], v[110:111], 1.0 op_sel_hi:[1,0]
	v_pk_add_f32 v[112:113], v[112:113], 1.0 op_sel_hi:[1,0]
	v_pk_add_f32 v[114:115], v[114:115], 1.0 op_sel_hi:[1,0]
	v_pk_mul_f32 v[68:69], v[68:69], v[118:119] op_sel_hi:[1,0]
	v_pk_mul_f32 v[70:71], v[70:71], v[118:119] op_sel_hi:[1,0]
	v_pk_mul_f32 v[72:73], v[72:73], v[118:119] op_sel_hi:[1,0]
	v_pk_mul_f32 v[74:75], v[74:75], v[118:119] op_sel_hi:[1,0]
	v_pk_mul_f32 v[76:77], v[76:77], v[118:119] op_sel_hi:[1,0]
	v_pk_mul_f32 v[78:79], v[78:79], v[118:119] op_sel_hi:[1,0]
	v_pk_mul_f32 v[80:81], v[80:81], v[118:119] op_sel_hi:[1,0]
	v_pk_mul_f32 v[82:83], v[82:83], v[118:119] op_sel_hi:[1,0]
	v_pk_mul_f32 v[68:69], v[4:5], v[68:69]
	v_pk_mul_f32 v[70:71], v[6:7], v[70:71]
	v_pk_mul_f32 v[72:73], v[8:9], v[72:73]
	v_pk_mul_f32 v[74:75], v[10:11], v[74:75]
	v_pk_mul_f32 v[76:77], v[12:13], v[76:77]
	v_pk_mul_f32 v[78:79], v[14:15], v[78:79]
	v_pk_mul_f32 v[80:81], v[16:17], v[80:81]
	v_pk_mul_f32 v[82:83], v[18:19], v[82:83]
	v_pk_fma_f32 v[68:69], v[100:101], v[68:69], v[84:85]
	v_pk_fma_f32 v[70:71], v[102:103], v[70:71], v[86:87]
	v_pk_fma_f32 v[72:73], v[104:105], v[72:73], v[88:89]
	v_pk_fma_f32 v[74:75], v[106:107], v[74:75], v[90:91]
	v_pk_fma_f32 v[76:77], v[108:109], v[76:77], v[92:93]
	v_pk_fma_f32 v[78:79], v[110:111], v[78:79], v[94:95]
	v_pk_fma_f32 v[80:81], v[112:113], v[80:81], v[96:97]
	v_pk_fma_f32 v[82:83], v[114:115], v[82:83], v[98:99]
	v_cvt_pk_bf16_f32 v68, v68, v69
	v_cvt_pk_bf16_f32 v69, v70, v71
	v_cvt_pk_bf16_f32 v72, v72, v73
	v_cvt_pk_bf16_f32 v73, v74, v75
	v_cvt_pk_bf16_f32 v76, v76, v77
	v_cvt_pk_bf16_f32 v77, v78, v79
	v_cvt_pk_bf16_f32 v80, v80, v81
	v_cvt_pk_bf16_f32 v81, v82, v83
	s_nop 1
	global_store_dwordx2 v3, v[68:69], s[16:17] offset:0
	global_store_dwordx2 v3, v[72:73], s[16:17] offset:512
	global_store_dwordx2 v3, v[76:77], s[16:17] offset:1024
	global_store_dwordx2 v3, v[80:81], s[16:17] offset:1536
.Lh1_noB2:
	s_add_i32 s2, s2, s5
	s_add_i32 s2, s2, s5
	s_cmp_lt_i32 s2, s3
	s_cbranch_scc1 .Lh1_loop
.Lh1_done:
	s_mov_b64 s[22:23], 0
.LBB0_104:
	s_movk_i32 s92, 0x4000
	s_or_b64 exec, exec, s[22:23]
	s_mov_b64 s[22:23], 0

; __device__ __forceinline__ int otid() { int t = threadIdx.x; asm volatile("" : "+v"(t)); return t; }
; __device__ __forceinline__ void phase_h(const Params& p, int c, int l, bf16_t* H) {
;     const int wave = otid() >> 6, lane = otid() & 63;
;     const int row0 = chunk_row0(c), n = chunk_rows(c);
;     const float* lng = p.in[4] + l * DM;
;     const float* mod_l = (const float*)(p.ws + WS_MOD) + (size_t)l * NSEQ * 3072;
;     for (int row = blockIdx.x * 8 + wave; row < n; row += gridDim.x * 8) {
.LBB0_106:
	s_and_b64 vcc, exec, s[24:25]
	s_cbranch_vccz .LBB0_112
	s_waitcnt lgkmcnt(0)
	v_readlane_b32 s2, v255, 15
	s_cmp_eq_u32 s2, 1
	s_mov_b64 s[22:23], -1
	s_cbranch_scc0 .LBB0_112
	v_readlane_b32 s2, v255, 15
	s_cmp_gt_u32 s2, 17
	s_cselect_b32 s7, 1, 0
	s_cmp_eq_u32 s2, 17
	s_cselect_b32 s7, 1, s7
	s_cmp_gt_u32 s2, 17
	s_cselect_b32 s3, 18, 2
	s_sub_i32 s3, s2, s3
	s_mul_i32 s3, s3, 0x3334
	s_lshr_b32 s3, s3, 16
	s_add_i32 s3, s3, 1
	s_cmp_eq_u32 s2, 1
	s_cselect_b32 s3, 0, s3
	s_cmp_eq_u32 s2, 17
	s_cselect_b32 s3, 0, s3
	s_lshl_b32 s6, s3, 15
	s_cmp_eq_u32 s3, 2
	s_movk_i32 s4, 0x4000
	s_cselect_b32 s3, s4, 0x8000
	v_readlane_b32 s4, v252, 21
	v_readlane_b32 s5, v252, 22
	s_nop 0
	s_load_dword s5, s[4:5], 0x0
	v_lshlrev_b32_e32 v2, 4, v219
	v_lshlrev_b32_e32 v3, 3, v219
	v_xor_b32_e32 v120, 16, v219
	v_lshlrev_b32_e32 v120, 2, v120
	v_readlane_b32 s2, v253, 43
	v_lshrrev_b32_e32 v0, 6, v251
	s_nop 0
	v_readfirstlane_b32 s4, v0
	s_add_i32 s2, s2, s4
	v_readlane_b32 s8, v252, 15
	v_readlane_b32 s9, v252, 16
	s_mul_i32 s4, s7, 0x6c000
	s_add_u32 s10, s8, 0x320dd900
	s_addc_u32 s11, s9, 0
	s_add_u32 s8, s8, 0x1d00000
	s_addc_u32 s9, s9, 0
	s_add_u32 s8, s8, s4
	s_addc_u32 s9, s9, 0
	v_readlane_b32 s16, v253, 52
	v_readlane_b32 s17, v253, 53
	s_lshl_b32 s4, s7, 12
	s_add_u32 s16, s16, s4
	s_addc_u32 s17, s17, 0
	s_nop 3
	global_load_dwordx4 v[4:7], v2, s[16:17] offset:0
	global_load_dwordx4 v[8:11], v2, s[16:17] offset:1024
	global_load_dwordx4 v[12:15], v2, s[16:17] offset:2048
	global_load_dwordx4 v[16:19], v2, s[16:17] offset:3072
	s_waitcnt lgkmcnt(0)
	s_lshl_b32 s5, s5, 3
	s_cmp_ge_i32 s2, s3
	s_cbranch_scc1 .Lh2_done

; __device__ __forceinline__ unsigned pk2(float lo, float hi) { f32x2 v = {lo, hi}; bf16x2_t b = __builtin_convertvector(v, bf16x2_t); return __builtin_bit_cast(unsigned, b); }
; __device__ __forceinline__ void phase_h(const Params& p, int c, int l, bf16_t* H) {
;     ...
;     for (int row = blockIdx.x * 8 + wave; row < n; row += gridDim.x * 8) {
;         const int g = row0 + row;
;         const float* xr = (l == 0) ? ((g < NPROMPT) ? p.in[0] + (size_t)g * DM : p.in[1] + (size_t)(g - NPROMPT) * DM) : p.out + (size_t)g * DM;
;         f32x4 v[4]; float ss = 0.f;
; #pragma unroll
;         for (int j = 0; j < 4; ++j) { v[j] = *(const f32x4*)(xr + j * 256 + lane * 4); ss += v[j][0] * v[j][0] + v[j][1] * v[j][1] + v[j][2] * v[j][2] + v[j][3] * v[j][3]; }
;         ss = wave_sum(ss);
;         const float rstd = rsqrtf(ss * (1.f / 1024.f) + EPS);
;         const float* md = mod_l + (size_t)seq_of(g) * 3072;
; #pragma unroll
;         for (int j = 0; j < 4; ++j) {
;             const int col = j * 256 + lane * 4;
;             const f32x4 gg = *(const f32x4*)(lng + col), sh = *(const f32x4*)(md + col), sc = *(const f32x4*)(md + 1024 + col);
;             const f32x4 h = v[j] * rstd * gg * (sc + 1.0f) + sh;
;             u32x2 o; o.x = pk2(h[0], h[1]); o.y = pk2(h[2], h[3]);
;             *(u32x2*)(H + (size_t)row * DM + col) = o;
;         }
;     }
.Lh2_done:
	s_mov_b64 s[22:23], 0
.LBB0_111:
	s_movk_i32 s92, 0x4000
	s_or_b64 exec, exec, s[22:23]
	s_mov_b64 s[22:23], 0

; __device__ __forceinline__ int otid() { int t = threadIdx.x; asm volatile("" : "+v"(t)); return t; }
; __device__ __forceinline__ void phase_h(const Params& p, int c, int l, bf16_t* H) {
;     const int wave = otid() >> 6, lane = otid() & 63;
;     const int row0 = chunk_row0(c), n = chunk_rows(c);
;     const float* lng = p.in[4] + l * DM;
;     const float* mod_l = (const float*)(p.ws + WS_MOD) + (size_t)l * NSEQ * 3072;
;     for (int row = blockIdx.x * 8 + wave; row < n; row += gridDim.x * 8) {
; __global__ void __launch_bounds__(NTHR, 2) mega(Params p) {
;     ...
;             if (c < 2) phase_h(p, c + 1, l, H);
.LBB0_440:
	v_readlane_b32 s0, v255, 19
	s_cmp_gt_i32 s0, 9
	s_cbranch_scc1 .LBB0_453
	v_readlane_b32 s2, v255, 15
	s_cmp_gt_u32 s2, 17
	s_cselect_b32 s7, 1, 0
	s_cmp_eq_u32 s2, 17
	s_cselect_b32 s7, 1, s7
	s_cmp_gt_u32 s2, 17
	s_cselect_b32 s3, 18, 2
	s_sub_i32 s3, s2, s3
	s_mul_i32 s3, s3, 0x3334
	s_lshr_b32 s3, s3, 16
	s_add_i32 s3, s3, 1
	s_cmp_eq_u32 s2, 1
	s_cselect_b32 s3, 0, s3
	s_cmp_eq_u32 s2, 17
	s_cselect_b32 s3, 0, s3
	s_lshl_b32 s6, s3, 15
	s_cmp_eq_u32 s3, 2
	s_movk_i32 s4, 0x4000
	s_cselect_b32 s3, s4, 0x8000
	v_readlane_b32 s4, v252, 21
	v_readlane_b32 s5, v252, 22
	s_nop 0
	s_load_dword s5, s[4:5], 0x0
	v_lshlrev_b32_e32 v2, 4, v219
	v_lshlrev_b32_e32 v3, 3, v219
	v_xor_b32_e32 v120, 16, v219
	v_lshlrev_b32_e32 v120, 2, v120
	v_readlane_b32 s2, v253, 43
	v_lshrrev_b32_e32 v0, 6, v251
	s_nop 0
	v_readfirstlane_b32 s4, v0
	s_add_i32 s2, s2, s4
	v_readlane_b32 s8, v252, 15
	v_readlane_b32 s9, v252, 16
	s_mul_i32 s4, s7, 0x6c000
	s_add_u32 s10, s8, 0x320dd900
	s_addc_u32 s11, s9, 0
	s_add_u32 s8, s8, 0x1d00000
	s_addc_u32 s9, s9, 0
	s_add_u32 s8, s8, s4
	s_addc_u32 s9, s9, 0
	v_readlane_b32 s16, v253, 52
	v_readlane_b32 s17, v253, 53
	s_lshl_b32 s4, s7, 12
	s_add_u32 s16, s16, s4
	s_addc_u32 s17, s17, 0
	s_nop 3
	global_load_dwordx4 v[4:7], v2, s[16:17] offset:0
	global_load_dwordx4 v[8:11], v2, s[16:17] offset:1024
	global_load_dwordx4 v[12:15], v2, s[16:17] offset:2048
	global_load_dwordx4 v[16:19], v2, s[16:17] offset:3072
	s_waitcnt lgkmcnt(0)
	s_lshl_b32 s5, s5, 3
	s_cmp_ge_i32 s2, s3
	s_cbranch_scc1 .Lh3_done

; __device__ __forceinline__ unsigned pk2(float lo, float hi) { f32x2 v = {lo, hi}; bf16x2_t b = __builtin_convertvector(v, bf16x2_t); return __builtin_bit_cast(unsigned, b); }
; __device__ __forceinline__ void phase_h(const Params& p, int c, int l, bf16_t* H) {
;     ...
;     for (int row = blockIdx.x * 8 + wave; row < n; row += gridDim.x * 8) {
;         const int g = row0 + row;
;         const float* xr = (l == 0) ? ((g < NPROMPT) ? p.in[0] + (size_t)g * DM : p.in[1] + (size_t)(g - NPROMPT) * DM) : p.out + (size_t)g * DM;
;         f32x4 v[4]; float ss = 0.f;
; #pragma unroll
;         for (int j = 0; j < 4; ++j) { v[j] = *(const f32x4*)(xr + j * 256 + lane * 4); ss += v[j][0] * v[j][0] + v[j][1] * v[j][1] + v[j][2] * v[j][2] + v[j][3] * v[j][3]; }
;         ss = wave_sum(ss);
;         const float rstd = rsqrtf(ss * (1.f / 1024.f) + EPS);
;         const float* md = mod_l + (size_t)seq_of(g) * 3072;
; #pragma unroll
;         for (int j = 0; j < 4; ++j) {
;             const int col = j * 256 + lane * 4;
;             const f32x4 gg = *(const f32x4*)(lng + col), sh = *(const f32x4*)(md + col), sc = *(const f32x4*)(md + 1024 + col);
;             const f32x4 h = v[j] * rstd * gg * (sc + 1.0f) + sh;
;             u32x2 o; o.x = pk2(h[0], h[1]); o.y = pk2(h[2], h[3]);
;             *(u32x2*)(H + (size_t)row * DM + col) = o;
;         }
;     }
.Lh3_done:
	s_branch .LBB0_453
.LBB0_452:
	s_or_b64 exec, exec, s[0:1]
